# P4 fused epilogue regenerated: row-sum exchange split into two row halves, its latency hidden behind the second half of the residual pass and the first half of the stores
# speedup vs baseline: 1.0178x; 1.0025x over previous
; #define LAS __attribute__((address_space(3)))
;     __device__ __forceinline__ void fused(f32x4 (&acc)[2][2][4][2], const Unit& u, int wr, int wc, int fr, int fq, LAS unsigned char* lds, int wid, int lane) const {
;         LAS float* Pq = (LAS float*)lds;
;         LAS float* S = (LAS float*)(lds + 4096);
;         const int row0 = u.pm * BM + wr * 64 + fr, col0 = u.pn * BM + wc * 32 + 4 * fq, b = u.pm >> 3;
;         f32x4 gv[2][2];
; #pragma unroll
;         for (int bj = 0; bj < 2; ++bj)
; #pragma unroll
;             for (int n = 0; n < 2; ++n) gv[bj][n] = *(const f32x4*)(ada + b * 3072 + 2048 + col0 + bj * HALF + n * 16);
; #pragma unroll
;         for (int ai = 0; ai < 2; ++ai)
; #pragma unroll
;             for (int m = 0; m < 4; ++m) { const int row = row0 + ai * HALF + m * 16; const size_t off = (size_t)row * DM + col0; float ss = 0.f;
; #pragma unroll
;                 for (int bj = 0; bj < 2; ++bj)
; #pragma unroll
;                     for (int n = 0; n < 2; ++n) { const f32x4 xv = *(const f32x4*)(x + off + bj * HALF + n * 16); const f32x4 o = xv + gv[bj][n] * acc[ai][bj][m][n];
;                         acc[ai][bj][m][n] = o; ss += (o[0] * o[0] + o[1] * o[1]) + (o[2] * o[2] + o[3] * o[3]); }
;                 ss += __shfl_xor(ss, 16); ss += __shfl_xor(ss, 32);
;                 if (fq == 0) Pq[(ai * HALF + wr * 64 + m * 16 + fr) * 4 + wc] = ss; }
.LBB0_435:
	s_lshl_b32 s0, s15, 5
	s_lshl_b32 s1, s16, 8
	s_or_b32 s0, s1, s0
	v_lshrrev_b32_e32 v128, 2, v150
	v_and_or_b32 v146, v128, 12, s0
	s_lshr_b32 s0, s14, 3
	s_mulk_i32 s0, 0xc00
	s_lshl_b32 s2, s14, 8
	s_ashr_i32 s1, s0, 31
	s_add_i32 s3, s2, s57
	s_lshl_b64 s[0:1], s[0:1], 2
	s_add_u32 s0, s22, s0
	v_ashrrev_i32_e32 v147, 31, v146
	s_addc_u32 s1, s23, s1
	v_lshlrev_b64 v[144:145], 2, v[146:147]
	v_lshl_add_u64 v[128:129], s[0:1], 0, v[144:145]
	s_mov_b64 s[0:1], 0x2000
	v_lshl_add_u64 v[140:141], v[128:129], 0, s[0:1]
	s_movk_i32 s0, 0x2000
	v_or_b32_e32 v148, s3, v148
	v_add_co_u32_e32 v128, vcc, s0, v128
	v_ashrrev_i32_e32 v149, 31, v148
	s_nop 0
	v_addc_co_u32_e32 v129, vcc, 0, v129, vcc
	v_lshlrev_b64 v[132:133], 12, v[148:149]
	s_barrier
	global_load_dwordx4 v[128:131], v[128:129], off
	v_lshl_add_u64 v[132:133], s[36:37], 0, v[132:133]
	v_lshl_add_u64 v[232:233], v[132:133], 0, v[144:145]
	global_load_dwordx4 v[136:139], v[140:141], off offset:64
	global_load_dwordx4 v[132:135], v[140:141], off offset:512
	global_load_dwordx4 v[140:143], v[140:141], off offset:576
	global_load_dwordx4 v[168:171], v[232:233], off
	global_load_dwordx4 v[172:175], v[232:233], off offset:64
	global_load_dwordx4 v[176:179], v[232:233], off offset:512
	global_load_dwordx4 v[180:183], v[232:233], off offset:576
	s_mov_b64 s[4:5], 0x10000
	v_lshl_add_u64 v[234:235], v[232:233], 0, s[4:5]
	global_load_dwordx4 v[184:187], v[234:235], off
	global_load_dwordx4 v[188:191], v[234:235], off offset:64
	global_load_dwordx4 v[192:195], v[234:235], off offset:512
	global_load_dwordx4 v[196:199], v[234:235], off offset:576
	s_mov_b64 s[4:5], 0x20000
	v_lshl_add_u64 v[234:235], v[232:233], 0, s[4:5]
	global_load_dwordx4 v[200:203], v[234:235], off
	global_load_dwordx4 v[204:207], v[234:235], off offset:64
	global_load_dwordx4 v[208:211], v[234:235], off offset:512
	global_load_dwordx4 v[212:215], v[234:235], off offset:576
	s_mov_b64 s[4:5], 0x30000
	v_lshl_add_u64 v[234:235], v[232:233], 0, s[4:5]
	global_load_dwordx4 v[216:219], v[234:235], off
	global_load_dwordx4 v[220:223], v[234:235], off offset:64
	global_load_dwordx4 v[224:227], v[234:235], off offset:512
	global_load_dwordx4 v[228:231], v[234:235], off offset:576
	v_and_b32_e32 v154, 63, v150
	v_mbcnt_lo_u32_b32 v150, -1, 0
	v_mbcnt_hi_u32_b32 v150, -1, v150
	v_and_b32_e32 v153, 64, v150
	v_xor_b32_e32 v151, 16, v150
	v_add_u32_e32 v153, 64, v153
	v_cmp_lt_i32_e32 vcc, v151, v153
	s_lshl_b32 s3, s15, 2
	s_add_i32 s3, s3, 0
	v_cndmask_b32_e32 v151, v150, v151, vcc
	v_lshlrev_b32_e32 v155, 2, v151
	v_cmp_gt_u32_e64 s[20:21], 16, v154
	v_xor_b32_e32 v157, 32, v150
	v_cmp_lt_i32_e32 vcc, v157, v153
	s_nop 1
	v_cndmask_b32_e32 v150, v150, v157, vcc
	v_lshlrev_b32_e32 v157, 2, v150
	v_lshl_add_u32 v156, v152, 4, s3
	s_waitcnt vmcnt(12)
	v_pk_fma_f32 v[124:125], v[124:125], v[128:129], v[168:169]
	v_pk_fma_f32 v[126:127], v[126:127], v[130:131], v[170:171]
	v_pk_fma_f32 v[120:121], v[120:121], v[136:137], v[172:173]
	v_pk_fma_f32 v[122:123], v[122:123], v[138:139], v[174:175]
	v_pk_fma_f32 v[116:117], v[116:117], v[132:133], v[176:177]
	v_pk_fma_f32 v[118:119], v[118:119], v[134:135], v[178:179]
	v_pk_fma_f32 v[112:113], v[112:113], v[140:141], v[180:181]
	v_pk_fma_f32 v[114:115], v[114:115], v[142:143], v[182:183]
	s_mov_b64 s[4:5], 0x80000
	v_lshl_add_u64 v[234:235], v[232:233], 0, s[4:5]
	global_load_dwordx4 v[168:171], v[234:235], off
	global_load_dwordx4 v[172:175], v[234:235], off offset:64
	global_load_dwordx4 v[176:179], v[234:235], off offset:512
	global_load_dwordx4 v[180:183], v[234:235], off offset:576
	v_mul_f32_e32 v240, v125, v125
	v_fmac_f32_e32 v240, v124, v124
	v_mul_f32_e32 v248, v127, v127
	v_fmac_f32_e32 v248, v126, v126
	v_mul_f32_e32 v249, v121, v121
	v_fmac_f32_e32 v249, v120, v120
	v_mul_f32_e32 v250, v123, v123
	v_fmac_f32_e32 v250, v122, v122
	v_mul_f32_e32 v251, v117, v117
	v_fmac_f32_e32 v251, v116, v116
	v_mul_f32_e32 v252, v119, v119
	v_fmac_f32_e32 v252, v118, v118
	v_mul_f32_e32 v253, v113, v113
	v_fmac_f32_e32 v253, v112, v112
	v_mul_f32_e32 v254, v115, v115
	v_fmac_f32_e32 v254, v114, v114
	v_add_f32_e32 v240, v240, v248
	v_add_f32_e32 v249, v249, v250
	v_add_f32_e32 v251, v251, v252
	v_add_f32_e32 v240, v240, v249
	v_add_f32_e32 v240, v240, v251
	v_add_f32_e32 v253, v253, v254
	v_add_f32_e32 v240, v240, v253
	s_waitcnt vmcnt(12)
	v_pk_fma_f32 v[108:109], v[108:109], v[128:129], v[184:185]
	v_pk_fma_f32 v[110:111], v[110:111], v[130:131], v[186:187]
	v_pk_fma_f32 v[104:105], v[104:105], v[136:137], v[188:189]
	v_pk_fma_f32 v[106:107], v[106:107], v[138:139], v[190:191]
	v_pk_fma_f32 v[100:101], v[100:101], v[132:133], v[192:193]
	v_pk_fma_f32 v[102:103], v[102:103], v[134:135], v[194:195]
	v_pk_fma_f32 v[96:97], v[96:97], v[140:141], v[196:197]
	v_pk_fma_f32 v[98:99], v[98:99], v[142:143], v[198:199]
	s_mov_b64 s[4:5], 0x90000
	v_lshl_add_u64 v[234:235], v[232:233], 0, s[4:5]
	global_load_dwordx4 v[184:187], v[234:235], off
	global_load_dwordx4 v[188:191], v[234:235], off offset:64
	global_load_dwordx4 v[192:195], v[234:235], off offset:512
	global_load_dwordx4 v[196:199], v[234:235], off offset:576
	v_mul_f32_e32 v241, v109, v109
	v_fmac_f32_e32 v241, v108, v108
	v_mul_f32_e32 v248, v111, v111
	v_fmac_f32_e32 v248, v110, v110
	v_mul_f32_e32 v249, v105, v105
	v_fmac_f32_e32 v249, v104, v104
	v_mul_f32_e32 v250, v107, v107
	v_fmac_f32_e32 v250, v106, v106
	v_mul_f32_e32 v251, v101, v101
	v_fmac_f32_e32 v251, v100, v100
	v_mul_f32_e32 v252, v103, v103
	v_fmac_f32_e32 v252, v102, v102
	v_mul_f32_e32 v253, v97, v97
	v_fmac_f32_e32 v253, v96, v96
	v_mul_f32_e32 v254, v99, v99
	v_fmac_f32_e32 v254, v98, v98
	v_add_f32_e32 v241, v241, v248
	v_add_f32_e32 v249, v249, v250
	v_add_f32_e32 v251, v251, v252
	v_add_f32_e32 v241, v241, v249
	v_add_f32_e32 v241, v241, v251
	v_add_f32_e32 v253, v253, v254
	v_add_f32_e32 v241, v241, v253
	s_waitcnt vmcnt(12)
; #define LAS __attribute__((address_space(3)))
; #define LDS_BARRIER() do { asm volatile("s_waitcnt lgkmcnt(0)" ::: "memory"); __builtin_amdgcn_s_barrier(); asm volatile("" ::: "memory"); } while (0)
;     __device__ __forceinline__ void fused(f32x4 (&acc)[2][2][4][2], const Unit& u, int wr, int wc, int fr, int fq, LAS unsigned char* lds, int wid, int lane) const {
;     ...
;         for (int ai = 0; ai < 2; ++ai)
; #pragma unroll
;             for (int m = 0; m < 4; ++m) { const int row = row0 + ai * HALF + m * 16; const size_t off = (size_t)row * DM + col0; float ss = 0.f;
; #pragma unroll
;                 for (int bj = 0; bj < 2; ++bj)
; #pragma unroll
;                     for (int n = 0; n < 2; ++n) { const f32x4 xv = *(const f32x4*)(x + off + bj * HALF + n * 16); const f32x4 o = xv + gv[bj][n] * acc[ai][bj][m][n];
;                         acc[ai][bj][m][n] = o; ss += (o[0] * o[0] + o[1] * o[1]) + (o[2] * o[2] + o[3] * o[3]); }
;                 ss += __shfl_xor(ss, 16); ss += __shfl_xor(ss, 32);
;                 if (fq == 0) Pq[(ai * HALF + wr * 64 + m * 16 + fr) * 4 + wc] = ss; }
;         LDS_BARRIER();
;         const int tid = wid * 64 + lane;
;         if (tid < 256) { const f32x4 p = *(const LAS f32x4*)(Pq + tid * 4);
;             __hip_atomic_store(xs + ((size_t)u.pm * 256 + tid) * 4 + u.pn, (p[0] + p[1]) + (p[2] + p[3]), __ATOMIC_RELAXED, __HIP_MEMORY_SCOPE_AGENT); }
	v_pk_fma_f32 v[92:93], v[92:93], v[128:129], v[200:201]
	v_pk_fma_f32 v[94:95], v[94:95], v[130:131], v[202:203]
	v_pk_fma_f32 v[88:89], v[88:89], v[136:137], v[204:205]
	v_pk_fma_f32 v[90:91], v[90:91], v[138:139], v[206:207]
	v_pk_fma_f32 v[84:85], v[84:85], v[132:133], v[208:209]
	v_pk_fma_f32 v[86:87], v[86:87], v[134:135], v[210:211]
	v_pk_fma_f32 v[80:81], v[80:81], v[140:141], v[212:213]
	v_pk_fma_f32 v[82:83], v[82:83], v[142:143], v[214:215]
	s_mov_b64 s[4:5], 0xa0000
	v_lshl_add_u64 v[234:235], v[232:233], 0, s[4:5]
	global_load_dwordx4 v[200:203], v[234:235], off
	global_load_dwordx4 v[204:207], v[234:235], off offset:64
	global_load_dwordx4 v[208:211], v[234:235], off offset:512
	global_load_dwordx4 v[212:215], v[234:235], off offset:576
	v_mul_f32_e32 v242, v93, v93
	v_fmac_f32_e32 v242, v92, v92
	v_mul_f32_e32 v248, v95, v95
	v_fmac_f32_e32 v248, v94, v94
	v_mul_f32_e32 v249, v89, v89
	v_fmac_f32_e32 v249, v88, v88
	v_mul_f32_e32 v250, v91, v91
	v_fmac_f32_e32 v250, v90, v90
	v_mul_f32_e32 v251, v85, v85
	v_fmac_f32_e32 v251, v84, v84
	v_mul_f32_e32 v252, v87, v87
	v_fmac_f32_e32 v252, v86, v86
	v_mul_f32_e32 v253, v81, v81
	v_fmac_f32_e32 v253, v80, v80
	v_mul_f32_e32 v254, v83, v83
	v_fmac_f32_e32 v254, v82, v82
	v_add_f32_e32 v242, v242, v248
	v_add_f32_e32 v249, v249, v250
	v_add_f32_e32 v251, v251, v252
	v_add_f32_e32 v242, v242, v249
	v_add_f32_e32 v242, v242, v251
	v_add_f32_e32 v253, v253, v254
	v_add_f32_e32 v242, v242, v253
	s_waitcnt vmcnt(12)
	v_pk_fma_f32 v[76:77], v[76:77], v[128:129], v[216:217]
	v_pk_fma_f32 v[78:79], v[78:79], v[130:131], v[218:219]
	v_pk_fma_f32 v[72:73], v[72:73], v[136:137], v[220:221]
	v_pk_fma_f32 v[74:75], v[74:75], v[138:139], v[222:223]
	v_pk_fma_f32 v[68:69], v[68:69], v[132:133], v[224:225]
	v_pk_fma_f32 v[70:71], v[70:71], v[134:135], v[226:227]
	v_pk_fma_f32 v[64:65], v[64:65], v[140:141], v[228:229]
	v_pk_fma_f32 v[66:67], v[66:67], v[142:143], v[230:231]
	v_mul_f32_e32 v243, v77, v77
	v_fmac_f32_e32 v243, v76, v76
	v_mul_f32_e32 v248, v79, v79
	v_fmac_f32_e32 v248, v78, v78
	v_mul_f32_e32 v249, v73, v73
	v_fmac_f32_e32 v249, v72, v72
	v_mul_f32_e32 v250, v75, v75
	v_fmac_f32_e32 v250, v74, v74
	v_mul_f32_e32 v251, v69, v69
	v_fmac_f32_e32 v251, v68, v68
	v_mul_f32_e32 v252, v71, v71
	v_fmac_f32_e32 v252, v70, v70
	v_mul_f32_e32 v253, v65, v65
	v_fmac_f32_e32 v253, v64, v64
	v_mul_f32_e32 v254, v67, v67
	v_fmac_f32_e32 v254, v66, v66
	v_add_f32_e32 v243, v243, v248
	v_add_f32_e32 v249, v249, v250
	v_add_f32_e32 v251, v251, v252
	v_add_f32_e32 v243, v243, v249
	v_add_f32_e32 v243, v243, v251
	v_add_f32_e32 v253, v253, v254
	v_add_f32_e32 v243, v243, v253
	ds_bpermute_b32 v158, v155, v240
	ds_bpermute_b32 v159, v155, v241
	ds_bpermute_b32 v160, v155, v242
	ds_bpermute_b32 v161, v155, v243
	s_waitcnt lgkmcnt(0)
	v_add_f32_e32 v240, v240, v158
	v_add_f32_e32 v241, v241, v159
	v_add_f32_e32 v242, v242, v160
	v_add_f32_e32 v243, v243, v161
	ds_bpermute_b32 v158, v157, v240
	ds_bpermute_b32 v159, v157, v241
	ds_bpermute_b32 v160, v157, v242
	ds_bpermute_b32 v161, v157, v243
	s_and_saveexec_b64 s[4:5], s[20:21]
	s_waitcnt lgkmcnt(0)
	v_add_f32_e32 v240, v240, v158
	ds_write_b32 v156, v240
	v_add_f32_e32 v241, v241, v159
	ds_write_b32 v156, v241 offset:256
	v_add_f32_e32 v242, v242, v160
	ds_write_b32 v156, v242 offset:512
	v_add_f32_e32 v243, v243, v161
	ds_write_b32 v156, v243 offset:768
	s_or_b64 exec, exec, s[4:5]
	s_waitcnt lgkmcnt(0)
	s_barrier
	s_lshr_b32 s4, s26, 1
	s_cmp_lg_u32 s4, 0
	s_cbranch_scc1 .Lp4x_pub0_skip
	v_add_u32_e32 v158, s25, v154
	v_lshlrev_b32_e32 v159, 4, v158
	ds_read_b128 v[160:163], v159
	s_lshl_b32 s4, s14, 12
	s_lshl_b32 s5, s16, 2
	s_add_u32 s4, s4, s5
	s_add_u32 s6, s12, s4
	s_addc_u32 s7, s13, 0
	s_waitcnt lgkmcnt(0)
	v_add_f32_e32 v160, v160, v161
	v_add_f32_e32 v162, v162, v163
	v_add_f32_e32 v160, v160, v162
	global_store_dword v159, v160, s[6:7] sc1
.Lp4x_pub0_skip:
	s_mov_b64 s[4:5], 0xb0000
	v_lshl_add_u64 v[234:235], v[232:233], 0, s[4:5]
	global_load_dwordx4 v[216:219], v[234:235], off
	global_load_dwordx4 v[220:223], v[234:235], off offset:64
	global_load_dwordx4 v[224:227], v[234:235], off offset:512
	global_load_dwordx4 v[228:231], v[234:235], off offset:576
	s_waitcnt vmcnt(12)
	v_pk_fma_f32 v[60:61], v[60:61], v[128:129], v[168:169]
	v_pk_fma_f32 v[62:63], v[62:63], v[130:131], v[170:171]
	v_pk_fma_f32 v[56:57], v[56:57], v[136:137], v[172:173]
	v_pk_fma_f32 v[58:59], v[58:59], v[138:139], v[174:175]
	v_pk_fma_f32 v[52:53], v[52:53], v[132:133], v[176:177]
	v_pk_fma_f32 v[54:55], v[54:55], v[134:135], v[178:179]
	v_pk_fma_f32 v[48:49], v[48:49], v[140:141], v[180:181]
	v_pk_fma_f32 v[50:51], v[50:51], v[142:143], v[182:183]
	v_mul_f32_e32 v244, v61, v61
	v_fmac_f32_e32 v244, v60, v60
	v_mul_f32_e32 v248, v63, v63
	v_fmac_f32_e32 v248, v62, v62
	v_mul_f32_e32 v249, v57, v57
	v_fmac_f32_e32 v249, v56, v56
	v_mul_f32_e32 v250, v59, v59
	v_fmac_f32_e32 v250, v58, v58
	v_mul_f32_e32 v251, v53, v53
	v_fmac_f32_e32 v251, v52, v52
	v_mul_f32_e32 v252, v55, v55
	v_fmac_f32_e32 v252, v54, v54
	v_mul_f32_e32 v253, v49, v49
	v_fmac_f32_e32 v253, v48, v48
	v_mul_f32_e32 v254, v51, v51
	v_fmac_f32_e32 v254, v50, v50
	v_add_f32_e32 v244, v244, v248
	v_add_f32_e32 v249, v249, v250
	v_add_f32_e32 v251, v251, v252
	v_add_f32_e32 v244, v244, v249
	v_add_f32_e32 v244, v244, v251
	v_add_f32_e32 v253, v253, v254
	v_add_f32_e32 v244, v244, v253
	s_waitcnt vmcnt(8)
; #define LAS __attribute__((address_space(3)))
; #define LDS_BARRIER() do { asm volatile("s_waitcnt lgkmcnt(0)" ::: "memory"); __builtin_amdgcn_s_barrier(); asm volatile("" ::: "memory"); } while (0)
;     __device__ __forceinline__ void fused(f32x4 (&acc)[2][2][4][2], const Unit& u, int wr, int wc, int fr, int fq, LAS unsigned char* lds, int wid, int lane) const {
;     ...
;         for (int ai = 0; ai < 2; ++ai)
; #pragma unroll
;             for (int m = 0; m < 4; ++m) { const int row = row0 + ai * HALF + m * 16; const size_t off = (size_t)row * DM + col0; float ss = 0.f;
; #pragma unroll
;                 for (int bj = 0; bj < 2; ++bj)
; #pragma unroll
;                     for (int n = 0; n < 2; ++n) { const f32x4 xv = *(const f32x4*)(x + off + bj * HALF + n * 16); const f32x4 o = xv + gv[bj][n] * acc[ai][bj][m][n];
;                         acc[ai][bj][m][n] = o; ss += (o[0] * o[0] + o[1] * o[1]) + (o[2] * o[2] + o[3] * o[3]); }
;                 ss += __shfl_xor(ss, 16); ss += __shfl_xor(ss, 32);
;                 if (fq == 0) Pq[(ai * HALF + wr * 64 + m * 16 + fr) * 4 + wc] = ss; }
;         LDS_BARRIER();
;         const int tid = wid * 64 + lane;
;         if (tid < 256) { const f32x4 p = *(const LAS f32x4*)(Pq + tid * 4);
;             __hip_atomic_store(xs + ((size_t)u.pm * 256 + tid) * 4 + u.pn, (p[0] + p[1]) + (p[2] + p[3]), __ATOMIC_RELAXED, __HIP_MEMORY_SCOPE_AGENT); }
;         asm volatile("s_waitcnt vmcnt(0)" ::: "memory");
;         if (wid < 4 && lane == 0) __hip_atomic_fetch_add(cnt + 64 * u.pm, 1u, __ATOMIC_RELAXED, __HIP_MEMORY_SCOPE_AGENT);
;         if (wid == 0) { unsigned sp = 0;
;             while ((unsigned)__builtin_amdgcn_readfirstlane(__hip_atomic_load(cnt + 64 * u.pm, __ATOMIC_RELAXED, __HIP_MEMORY_SCOPE_AGENT)) < 16u) { __builtin_amdgcn_s_sleep(1); if (++sp > (1u << 20)) break; }
;             __builtin_amdgcn_fence(__ATOMIC_ACQUIRE, "agent");
;             asm volatile("s_waitcnt vmcnt(0)" ::: "memory"); }
;         LDS_BARRIER();
;     ...
;             for (int n = 0; n < 2; ++n) fgv[bj][n] = *(const f32x4*)(fg + col0 + bj * HALF + n * 16);
	v_pk_fma_f32 v[44:45], v[44:45], v[128:129], v[184:185]
	v_pk_fma_f32 v[46:47], v[46:47], v[130:131], v[186:187]
	v_pk_fma_f32 v[40:41], v[40:41], v[136:137], v[188:189]
	v_pk_fma_f32 v[42:43], v[42:43], v[138:139], v[190:191]
	v_pk_fma_f32 v[36:37], v[36:37], v[132:133], v[192:193]
	v_pk_fma_f32 v[38:39], v[38:39], v[134:135], v[194:195]
	v_pk_fma_f32 v[32:33], v[32:33], v[140:141], v[196:197]
	v_pk_fma_f32 v[34:35], v[34:35], v[142:143], v[198:199]
	v_mul_f32_e32 v245, v45, v45
	v_fmac_f32_e32 v245, v44, v44
	v_mul_f32_e32 v248, v47, v47
	v_fmac_f32_e32 v248, v46, v46
	v_mul_f32_e32 v249, v41, v41
	v_fmac_f32_e32 v249, v40, v40
	v_mul_f32_e32 v250, v43, v43
	v_fmac_f32_e32 v250, v42, v42
	v_mul_f32_e32 v251, v37, v37
	v_fmac_f32_e32 v251, v36, v36
	v_mul_f32_e32 v252, v39, v39
	v_fmac_f32_e32 v252, v38, v38
	v_mul_f32_e32 v253, v33, v33
	v_fmac_f32_e32 v253, v32, v32
	v_mul_f32_e32 v254, v35, v35
	v_fmac_f32_e32 v254, v34, v34
	v_add_f32_e32 v245, v245, v248
	v_add_f32_e32 v249, v249, v250
	v_add_f32_e32 v251, v251, v252
	v_add_f32_e32 v245, v245, v249
	v_add_f32_e32 v245, v245, v251
	v_add_f32_e32 v253, v253, v254
	v_add_f32_e32 v245, v245, v253
	s_waitcnt vmcnt(4)
	v_pk_fma_f32 v[28:29], v[28:29], v[128:129], v[200:201]
	v_pk_fma_f32 v[30:31], v[30:31], v[130:131], v[202:203]
	v_pk_fma_f32 v[24:25], v[24:25], v[136:137], v[204:205]
	v_pk_fma_f32 v[26:27], v[26:27], v[138:139], v[206:207]
	v_pk_fma_f32 v[20:21], v[20:21], v[132:133], v[208:209]
	v_pk_fma_f32 v[22:23], v[22:23], v[134:135], v[210:211]
	v_pk_fma_f32 v[16:17], v[16:17], v[140:141], v[212:213]
	v_pk_fma_f32 v[18:19], v[18:19], v[142:143], v[214:215]
	v_mul_f32_e32 v246, v29, v29
	v_fmac_f32_e32 v246, v28, v28
	v_mul_f32_e32 v248, v31, v31
	v_fmac_f32_e32 v248, v30, v30
	v_mul_f32_e32 v249, v25, v25
	v_fmac_f32_e32 v249, v24, v24
	v_mul_f32_e32 v250, v27, v27
	v_fmac_f32_e32 v250, v26, v26
	v_mul_f32_e32 v251, v21, v21
	v_fmac_f32_e32 v251, v20, v20
	v_mul_f32_e32 v252, v23, v23
	v_fmac_f32_e32 v252, v22, v22
	v_mul_f32_e32 v253, v17, v17
	v_fmac_f32_e32 v253, v16, v16
	v_mul_f32_e32 v254, v19, v19
	v_fmac_f32_e32 v254, v18, v18
	v_add_f32_e32 v246, v246, v248
	v_add_f32_e32 v249, v249, v250
	v_add_f32_e32 v251, v251, v252
	v_add_f32_e32 v246, v246, v249
	v_add_f32_e32 v246, v246, v251
	v_add_f32_e32 v253, v253, v254
	v_add_f32_e32 v246, v246, v253
	s_lshr_b32 s4, s26, 1
	s_cmp_lg_u32 s4, 0
	s_cbranch_scc1 .Lp4x_sig0_skip
	v_cmp_eq_u32_e32 vcc, 0, v154
	s_and_saveexec_b64 s[4:5], vcc
	s_lshl_b32 s6, s14, 8
	s_add_u32 s6, s6, 0x84000
	s_add_u32 s6, s22, s6
	s_addc_u32 s7, s23, 0
	v_mov_b32_e32 v158, 0
	v_mov_b32_e32 v159, 1
	global_atomic_add v158, v159, s[6:7]
	s_or_b64 exec, exec, s[4:5]
.Lp4x_sig0_skip:
	s_waitcnt vmcnt(0)
	v_pk_fma_f32 v[148:149], v[12:13], v[128:129], v[216:217]
	v_pk_fma_f32 v[146:147], v[14:15], v[130:131], v[218:219]
	v_pk_fma_f32 v[136:137], v[8:9], v[136:137], v[220:221]
	v_pk_fma_f32 v[138:139], v[10:11], v[138:139], v[222:223]
	v_pk_fma_f32 v[132:133], v[4:5], v[132:133], v[224:225]
	v_pk_fma_f32 v[134:135], v[6:7], v[134:135], v[226:227]
	v_pk_fma_f32 v[130:131], v[0:1], v[140:141], v[228:229]
	v_pk_fma_f32 v[128:129], v[2:3], v[142:143], v[230:231]
	v_mul_f32_e32 v247, v149, v149
	v_fmac_f32_e32 v247, v148, v148
	v_mul_f32_e32 v248, v147, v147
	v_fmac_f32_e32 v248, v146, v146
	v_mul_f32_e32 v249, v137, v137
	v_fmac_f32_e32 v249, v136, v136
	v_mul_f32_e32 v250, v139, v139
	v_fmac_f32_e32 v250, v138, v138
	v_mul_f32_e32 v251, v133, v133
	v_fmac_f32_e32 v251, v132, v132
	v_mul_f32_e32 v252, v135, v135
	v_fmac_f32_e32 v252, v134, v134
	v_mul_f32_e32 v253, v131, v131
	v_fmac_f32_e32 v253, v130, v130
	v_mul_f32_e32 v254, v129, v129
	v_fmac_f32_e32 v254, v128, v128
	v_add_f32_e32 v247, v247, v248
	v_add_f32_e32 v249, v249, v250
	v_add_f32_e32 v251, v251, v252
	v_add_f32_e32 v247, v247, v249
	v_add_f32_e32 v247, v247, v251
	v_add_f32_e32 v253, v253, v254
	v_add_f32_e32 v247, v247, v253
	v_lshl_add_u64 v[236:237], s[92:93], 0, v[144:145]
	global_load_dwordx4 v[168:171], v[236:237], off
	global_load_dwordx4 v[172:175], v[236:237], off offset:64
	global_load_dwordx4 v[176:179], v[236:237], off offset:512
	global_load_dwordx4 v[180:183], v[236:237], off offset:576
	ds_bpermute_b32 v158, v155, v244
	ds_bpermute_b32 v159, v155, v245
	ds_bpermute_b32 v160, v155, v246
	ds_bpermute_b32 v161, v155, v247
	s_waitcnt lgkmcnt(0)
	v_add_f32_e32 v244, v244, v158
	v_add_f32_e32 v245, v245, v159
	v_add_f32_e32 v246, v246, v160
	v_add_f32_e32 v247, v247, v161
	ds_bpermute_b32 v158, v157, v244
	ds_bpermute_b32 v159, v157, v245
	ds_bpermute_b32 v160, v157, v246
	ds_bpermute_b32 v161, v157, v247
	s_and_saveexec_b64 s[4:5], s[20:21]
	s_waitcnt lgkmcnt(0)
	v_add_f32_e32 v244, v244, v158
	ds_write_b32 v156, v244 offset:2048
	v_add_f32_e32 v245, v245, v159
	ds_write_b32 v156, v245 offset:2304
	v_add_f32_e32 v246, v246, v160
	ds_write_b32 v156, v246 offset:2560
	v_add_f32_e32 v247, v247, v161
	ds_write_b32 v156, v247 offset:2816
	s_or_b64 exec, exec, s[4:5]
	s_cmp_lg_u32 s26, 0
	s_cbranch_scc1 .Lp4x_wait0_done
	s_lshl_b32 s6, s14, 8
	s_add_u32 s6, s6, 0x84000
	s_add_u32 s6, s22, s6
	s_addc_u32 s7, s23, 0
	s_mov_b32 s17, 0x100001
	v_mov_b32_e32 v158, 0
; #define LAS __attribute__((address_space(3)))
; #define LDS_BARRIER() do { asm volatile("s_waitcnt lgkmcnt(0)" ::: "memory"); __builtin_amdgcn_s_barrier(); asm volatile("" ::: "memory"); } while (0)
;     __device__ __forceinline__ void fused(f32x4 (&acc)[2][2][4][2], const Unit& u, int wr, int wc, int fr, int fq, LAS unsigned char* lds, int wid, int lane) const {
;     ...
;         LDS_BARRIER();
;         const int tid = wid * 64 + lane;
;         if (tid < 256) { const f32x4 p = *(const LAS f32x4*)(Pq + tid * 4);
;             __hip_atomic_store(xs + ((size_t)u.pm * 256 + tid) * 4 + u.pn, (p[0] + p[1]) + (p[2] + p[3]), __ATOMIC_RELAXED, __HIP_MEMORY_SCOPE_AGENT); }
;         asm volatile("s_waitcnt vmcnt(0)" ::: "memory");
;         if (wid < 4 && lane == 0) __hip_atomic_fetch_add(cnt + 64 * u.pm, 1u, __ATOMIC_RELAXED, __HIP_MEMORY_SCOPE_AGENT);
;         if (wid == 0) { unsigned sp = 0;
;             while ((unsigned)__builtin_amdgcn_readfirstlane(__hip_atomic_load(cnt + 64 * u.pm, __ATOMIC_RELAXED, __HIP_MEMORY_SCOPE_AGENT)) < 16u) { __builtin_amdgcn_s_sleep(1); if (++sp > (1u << 20)) break; }
;             __builtin_amdgcn_fence(__ATOMIC_ACQUIRE, "agent");
;             asm volatile("s_waitcnt vmcnt(0)" ::: "memory"); }
;         LDS_BARRIER();
;         if (tid < 256) { const float* sp = xs + ((size_t)u.pm * 256 + tid) * 4; float t = 0.f;
; #pragma unroll
;             for (int k = 0; k < 4; ++k) t += __hip_atomic_load(sp + k, __ATOMIC_RELAXED, __HIP_MEMORY_SCOPE_AGENT);
;             S[tid] = 1.0f / sqrtf(t * (1.0f / DM) + 1e-6f); }
;         LDS_BARRIER();
.Lp4x_wait0_loop:
	global_load_dword v159, v158, s[6:7] sc1
	s_waitcnt vmcnt(0)
	v_readfirstlane_b32 s4, v159
	s_cmp_gt_u32 s4, 7
	s_cbranch_scc1 .Lp4x_wait0_done
	s_add_i32 s17, s17, -1
	s_cmp_eq_u32 s17, 0
	s_cbranch_scc1 .Lp4x_wait0_done
	s_sleep 1
	s_branch .Lp4x_wait0_loop
.Lp4x_wait0_done:
	s_waitcnt lgkmcnt(0)
	s_barrier
	s_cmp_gt_u32 s26, 1
	s_cbranch_scc1 .Lp4x_rstdA_skip
	s_lshl_b32 s4, s14, 12
	s_add_u32 s6, s12, s4
	s_addc_u32 s7, s13, 0
	s_mov_b32 s18, 0xf800000
	v_add_u32_e32 v158, s25, v154
	v_lshlrev_b32_e32 v159, 4, v158
	global_load_dwordx4 v[240:243], v159, s[6:7] sc1
	s_waitcnt vmcnt(0)
	v_add_f32_e32 v240, 0, v240
	v_add_f32_e32 v240, v240, v241
	v_add_f32_e32 v240, v240, v242
	v_add_f32_e32 v240, v240, v243
	v_mov_b32_e32 v248, 0x358637bd
	v_fmac_f32_e32 v248, 0x3a800000, v240
	v_mul_f32_e32 v240, 0x4f800000, v248
	v_cmp_gt_f32_e32 vcc, s18, v248
	s_nop 1
	v_cndmask_b32_e32 v240, v248, v240, vcc
	v_sqrt_f32_e32 v249, v240
	v_mov_b32_e32 v248, 0x260
	v_add_u32_e32 v250, -1, v249
	v_add_u32_e32 v251, 1, v249
	v_fma_f32 v252, -v250, v249, v240
	v_fma_f32 v253, -v251, v249, v240
	v_cmp_ge_f32_e64 s[4:5], 0, v252
	s_nop 1
	v_cndmask_b32_e64 v249, v249, v250, s[4:5]
	v_cmp_lt_f32_e64 s[4:5], 0, v253
	s_nop 1
	v_cndmask_b32_e64 v249, v249, v251, s[4:5]
	v_mul_f32_e32 v250, 0x37800000, v249
	v_cndmask_b32_e32 v249, v249, v250, vcc
	v_cmp_class_f32_e32 vcc, v240, v248
	s_nop 1
	v_cndmask_b32_e32 v240, v249, v240, vcc
	v_div_scale_f32 v249, s[4:5], v240, v240, 1.0
	v_rcp_f32_e32 v248, v249
	v_div_scale_f32 v250, vcc, 1.0, v240, 1.0
	v_fma_f32 v251, -v249, v248, 1.0
	v_fmac_f32_e32 v248, v251, v248
	v_mul_f32_e32 v251, v250, v248
	v_fma_f32 v252, -v249, v251, v250
	v_fmac_f32_e32 v251, v252, v248
	v_fma_f32 v249, -v249, v251, v250
	v_div_fmas_f32 v249, v249, v248, v251
	v_div_fixup_f32 v240, v249, v240, 1.0
	v_lshlrev_b32_e32 v254, 2, v158
	ds_write_b32 v254, v240 offset:4096
.Lp4x_rstdA_skip:
	s_lshr_b32 s4, s26, 1
	s_cmp_lg_u32 s4, 1
	s_cbranch_scc1 .Lp4x_pub1_skip
	v_add_u32_e32 v158, s25, v154
	v_lshlrev_b32_e32 v159, 4, v158
	ds_read_b128 v[160:163], v159
	s_lshl_b32 s4, s14, 12
	s_lshl_b32 s5, s16, 2
	s_add_u32 s4, s4, s5
	s_add_u32 s6, s12, s4
	s_addc_u32 s7, s13, 0
	s_waitcnt lgkmcnt(0)
	v_add_f32_e32 v160, v160, v161
	v_add_f32_e32 v162, v162, v163
	v_add_f32_e32 v160, v160, v162
	global_store_dword v159, v160, s[6:7] sc1
.Lp4x_pub1_skip:
	s_waitcnt vmcnt(0)
	s_lshr_b32 s4, s26, 1
	s_cmp_lg_u32 s4, 1
	s_cbranch_scc1 .Lp4x_sig1_skip
	v_cmp_eq_u32_e32 vcc, 0, v154
	s_and_saveexec_b64 s[4:5], vcc
	s_lshl_b32 s6, s14, 8
	s_add_u32 s6, s6, 0x84004
	s_add_u32 s6, s22, s6
	s_addc_u32 s7, s23, 0
	v_mov_b32_e32 v158, 0
	v_mov_b32_e32 v159, 1
	global_atomic_add v158, v159, s[6:7]
	s_or_b64 exec, exec, s[4:5]
.Lp4x_sig1_skip:
	s_waitcnt lgkmcnt(0)
	s_barrier
	s_cmp_lg_u32 s26, 0
	s_cbranch_scc1 .Lp4x_rstdB_skip
	s_cmp_lg_u32 s26, 0
	s_cbranch_scc1 .Lp4x_wait1_done
	s_lshl_b32 s6, s14, 8
	s_add_u32 s6, s6, 0x84004
	s_add_u32 s6, s22, s6
	s_addc_u32 s7, s23, 0
	s_mov_b32 s17, 0x100001
	v_mov_b32_e32 v158, 0

; #define LDS_BARRIER() do { asm volatile("s_waitcnt lgkmcnt(0)" ::: "memory"); __builtin_amdgcn_s_barrier(); asm volatile("" ::: "memory"); } while (0)
;     __device__ __forceinline__ void fused(f32x4 (&acc)[2][2][4][2], const Unit& u, int wr, int wc, int fr, int fq, LAS unsigned char* lds, int wid, int lane) const {
;     ...
;         if (tid < 256) { const float* sp = xs + ((size_t)u.pm * 256 + tid) * 4; float t = 0.f;
; #pragma unroll
;             for (int k = 0; k < 4; ++k) t += __hip_atomic_load(sp + k, __ATOMIC_RELAXED, __HIP_MEMORY_SCOPE_AGENT);
;             S[tid] = 1.0f / sqrtf(t * (1.0f / DM) + 1e-6f); }
;         LDS_BARRIER();
;         f32x4 fgv[2][2];
; #pragma unroll
;         for (int bj = 0; bj < 2; ++bj)
; #pragma unroll
;             for (int n = 0; n < 2; ++n) fgv[bj][n] = *(const f32x4*)(fg + col0 + bj * HALF + n * 16);
; #pragma unroll
;         for (int ai = 0; ai < 2; ++ai)
; #pragma unroll
;             for (int m = 0; m < 4; ++m) { const int rl = ai * HALF + wr * 64 + m * 16 + fr; const float r = S[rl]; const size_t off = (size_t)(u.pm * BM + rl) * DM + col0;
; #pragma unroll
;                 for (int bj = 0; bj < 2; ++bj)
; #pragma unroll
;                     for (int n = 0; n < 2; ++n) *(f32x4*)(out + off + bj * HALF + n * 16) = acc[ai][bj][m][n] * r * fgv[bj][n]; }
.Lp4x_wait1_done:
	s_lshl_b32 s4, s14, 12
	s_add_u32 s6, s12, s4
	s_addc_u32 s7, s13, 0
	s_mov_b32 s18, 0xf800000
	v_add_u32_e32 v158, 0x80, v154
	v_lshlrev_b32_e32 v159, 4, v158
	global_load_dwordx4 v[240:243], v159, s[6:7] sc1
	v_add_u32_e32 v159, 0x400, v159
	global_load_dwordx4 v[244:247], v159, s[6:7] sc1
	s_waitcnt vmcnt(1)
	v_add_f32_e32 v240, 0, v240
	v_add_f32_e32 v240, v240, v241
	v_add_f32_e32 v240, v240, v242
	v_add_f32_e32 v240, v240, v243
	v_mov_b32_e32 v248, 0x358637bd
	v_fmac_f32_e32 v248, 0x3a800000, v240
	v_mul_f32_e32 v240, 0x4f800000, v248
	v_cmp_gt_f32_e32 vcc, s18, v248
	s_nop 1
	v_cndmask_b32_e32 v240, v248, v240, vcc
	v_sqrt_f32_e32 v249, v240
	v_mov_b32_e32 v248, 0x260
	v_add_u32_e32 v250, -1, v249
	v_add_u32_e32 v251, 1, v249
	v_fma_f32 v252, -v250, v249, v240
	v_fma_f32 v253, -v251, v249, v240
	v_cmp_ge_f32_e64 s[4:5], 0, v252
	s_nop 1
	v_cndmask_b32_e64 v249, v249, v250, s[4:5]
	v_cmp_lt_f32_e64 s[4:5], 0, v253
	s_nop 1
	v_cndmask_b32_e64 v249, v249, v251, s[4:5]
	v_mul_f32_e32 v250, 0x37800000, v249
	v_cndmask_b32_e32 v249, v249, v250, vcc
	v_cmp_class_f32_e32 vcc, v240, v248
	s_nop 1
	v_cndmask_b32_e32 v240, v249, v240, vcc
	v_div_scale_f32 v249, s[4:5], v240, v240, 1.0
	v_rcp_f32_e32 v248, v249
	v_div_scale_f32 v250, vcc, 1.0, v240, 1.0
	v_fma_f32 v251, -v249, v248, 1.0
	v_fmac_f32_e32 v248, v251, v248
	v_mul_f32_e32 v251, v250, v248
	v_fma_f32 v252, -v249, v251, v250
	v_fmac_f32_e32 v251, v252, v248
	v_fma_f32 v249, -v249, v251, v250
	v_div_fmas_f32 v249, v249, v248, v251
	v_div_fixup_f32 v240, v249, v240, 1.0
	v_lshlrev_b32_e32 v254, 2, v158
	ds_write_b32 v254, v240 offset:4096
	s_waitcnt vmcnt(0)
	v_add_f32_e32 v244, 0, v244
	v_add_f32_e32 v244, v244, v245
	v_add_f32_e32 v244, v244, v246
	v_add_f32_e32 v244, v244, v247
	v_mov_b32_e32 v248, 0x358637bd
	v_fmac_f32_e32 v248, 0x3a800000, v244
	v_mul_f32_e32 v244, 0x4f800000, v248
	v_cmp_gt_f32_e32 vcc, s18, v248
	s_nop 1
	v_cndmask_b32_e32 v244, v248, v244, vcc
	v_sqrt_f32_e32 v249, v244
	v_mov_b32_e32 v248, 0x260
	v_add_u32_e32 v250, -1, v249
	v_add_u32_e32 v251, 1, v249
	v_fma_f32 v252, -v250, v249, v244
	v_fma_f32 v253, -v251, v249, v244
	v_cmp_ge_f32_e64 s[4:5], 0, v252
	s_nop 1
	v_cndmask_b32_e64 v249, v249, v250, s[4:5]
	v_cmp_lt_f32_e64 s[4:5], 0, v253
	s_nop 1
	v_cndmask_b32_e64 v249, v249, v251, s[4:5]
	v_mul_f32_e32 v250, 0x37800000, v249
	v_cndmask_b32_e32 v249, v249, v250, vcc
	v_cmp_class_f32_e32 vcc, v244, v248
	s_nop 1
	v_cndmask_b32_e32 v244, v249, v244, vcc
	v_div_scale_f32 v249, s[4:5], v244, v244, 1.0
	v_rcp_f32_e32 v248, v249
	v_div_scale_f32 v250, vcc, 1.0, v244, 1.0
	v_fma_f32 v251, -v249, v248, 1.0
	v_fmac_f32_e32 v248, v251, v248
	v_mul_f32_e32 v251, v250, v248
	v_fma_f32 v252, -v249, v251, v250
	v_fmac_f32_e32 v251, v252, v248
	v_fma_f32 v249, -v249, v251, v250
	v_div_fmas_f32 v249, v249, v248, v251
	v_div_fixup_f32 v244, v249, v244, 1.0
	v_lshlrev_b32_e32 v254, 2, v158
	ds_write_b32 v254, v244 offset:4352
.Lp4x_rstdB_skip:
	v_add_u32_e32 v236, s2, v152
	v_mov_b32_e32 v237, 0
	v_lshlrev_b64 v[236:237], 12, v[236:237]
	v_lshl_add_u64 v[232:233], s[94:95], 0, v[236:237]
	v_lshl_add_u64 v[232:233], v[232:233], 0, v[144:145]
	v_lshlrev_b32_e32 v238, 2, v152
	s_waitcnt vmcnt(0) lgkmcnt(0)
	ds_read_b32 v216, v238 offset:4096
	ds_read_b32 v218, v238 offset:4160
	ds_read_b32 v220, v238 offset:4224
	ds_read_b32 v222, v238 offset:4288
	s_waitcnt lgkmcnt(3)
	v_pk_mul_f32 v[184:185], v[124:125], v[216:217] op_sel_hi:[1,0]
	v_pk_mul_f32 v[186:187], v[126:127], v[216:217] op_sel_hi:[1,0]
	v_pk_mul_f32 v[188:189], v[120:121], v[216:217] op_sel_hi:[1,0]
	v_pk_mul_f32 v[190:191], v[122:123], v[216:217] op_sel_hi:[1,0]
	v_pk_mul_f32 v[192:193], v[116:117], v[216:217] op_sel_hi:[1,0]
	v_pk_mul_f32 v[194:195], v[118:119], v[216:217] op_sel_hi:[1,0]
	v_pk_mul_f32 v[196:197], v[112:113], v[216:217] op_sel_hi:[1,0]
	v_pk_mul_f32 v[198:199], v[114:115], v[216:217] op_sel_hi:[1,0]
	v_pk_mul_f32 v[184:185], v[168:169], v[184:185]
	v_pk_mul_f32 v[186:187], v[170:171], v[186:187]
	v_pk_mul_f32 v[188:189], v[172:173], v[188:189]
	v_pk_mul_f32 v[190:191], v[174:175], v[190:191]
	v_pk_mul_f32 v[192:193], v[176:177], v[192:193]
	v_pk_mul_f32 v[194:195], v[178:179], v[194:195]
	v_pk_mul_f32 v[196:197], v[180:181], v[196:197]
	v_pk_mul_f32 v[198:199], v[182:183], v[198:199]
	global_store_dwordx4 v[232:233], v[184:187], off
	global_store_dwordx4 v[232:233], v[188:191], off offset:64
	global_store_dwordx4 v[232:233], v[192:195], off offset:512
	global_store_dwordx4 v[232:233], v[196:199], off offset:576
	s_waitcnt lgkmcnt(2)
	v_pk_mul_f32 v[200:201], v[108:109], v[218:219] op_sel_hi:[1,0]
	v_pk_mul_f32 v[202:203], v[110:111], v[218:219] op_sel_hi:[1,0]
	v_pk_mul_f32 v[204:205], v[104:105], v[218:219] op_sel_hi:[1,0]
	v_pk_mul_f32 v[206:207], v[106:107], v[218:219] op_sel_hi:[1,0]
	v_pk_mul_f32 v[208:209], v[100:101], v[218:219] op_sel_hi:[1,0]
	v_pk_mul_f32 v[210:211], v[102:103], v[218:219] op_sel_hi:[1,0]
	v_pk_mul_f32 v[212:213], v[96:97], v[218:219] op_sel_hi:[1,0]
	v_pk_mul_f32 v[214:215], v[98:99], v[218:219] op_sel_hi:[1,0]
	v_pk_mul_f32 v[200:201], v[168:169], v[200:201]
	v_pk_mul_f32 v[202:203], v[170:171], v[202:203]
	v_pk_mul_f32 v[204:205], v[172:173], v[204:205]
	v_pk_mul_f32 v[206:207], v[174:175], v[206:207]
	v_pk_mul_f32 v[208:209], v[176:177], v[208:209]
	v_pk_mul_f32 v[210:211], v[178:179], v[210:211]
	v_pk_mul_f32 v[212:213], v[180:181], v[212:213]
	v_pk_mul_f32 v[214:215], v[182:183], v[214:215]
	s_mov_b64 s[4:5], 0x10000
	v_lshl_add_u64 v[234:235], v[232:233], 0, s[4:5]
	global_store_dwordx4 v[234:235], v[200:203], off
	global_store_dwordx4 v[234:235], v[204:207], off offset:64
	global_store_dwordx4 v[234:235], v[208:211], off offset:512
	global_store_dwordx4 v[234:235], v[212:215], off offset:576
	s_waitcnt lgkmcnt(1)
;     __device__ __forceinline__ void fused(f32x4 (&acc)[2][2][4][2], const Unit& u, int wr, int wc, int fr, int fq, LAS unsigned char* lds, int wid, int lane) const {
;     ...
;         for (int ai = 0; ai < 2; ++ai)
; #pragma unroll
;             for (int m = 0; m < 4; ++m) { const int rl = ai * HALF + wr * 64 + m * 16 + fr; const float r = S[rl]; const size_t off = (size_t)(u.pm * BM + rl) * DM + col0;
; #pragma unroll
;                 for (int bj = 0; bj < 2; ++bj)
; #pragma unroll
;                     for (int n = 0; n < 2; ++n) *(f32x4*)(out + off + bj * HALF + n * 16) = acc[ai][bj][m][n] * r * fgv[bj][n]; }
	v_pk_mul_f32 v[184:185], v[92:93], v[220:221] op_sel_hi:[1,0]
	v_pk_mul_f32 v[186:187], v[94:95], v[220:221] op_sel_hi:[1,0]
	v_pk_mul_f32 v[188:189], v[88:89], v[220:221] op_sel_hi:[1,0]
	v_pk_mul_f32 v[190:191], v[90:91], v[220:221] op_sel_hi:[1,0]
	v_pk_mul_f32 v[192:193], v[84:85], v[220:221] op_sel_hi:[1,0]
	v_pk_mul_f32 v[194:195], v[86:87], v[220:221] op_sel_hi:[1,0]
	v_pk_mul_f32 v[196:197], v[80:81], v[220:221] op_sel_hi:[1,0]
	v_pk_mul_f32 v[198:199], v[82:83], v[220:221] op_sel_hi:[1,0]
	v_pk_mul_f32 v[184:185], v[168:169], v[184:185]
	v_pk_mul_f32 v[186:187], v[170:171], v[186:187]
	v_pk_mul_f32 v[188:189], v[172:173], v[188:189]
	v_pk_mul_f32 v[190:191], v[174:175], v[190:191]
	v_pk_mul_f32 v[192:193], v[176:177], v[192:193]
	v_pk_mul_f32 v[194:195], v[178:179], v[194:195]
	v_pk_mul_f32 v[196:197], v[180:181], v[196:197]
	v_pk_mul_f32 v[198:199], v[182:183], v[198:199]
	s_mov_b64 s[4:5], 0x20000
	v_lshl_add_u64 v[234:235], v[232:233], 0, s[4:5]
	global_store_dwordx4 v[234:235], v[184:187], off
	global_store_dwordx4 v[234:235], v[188:191], off offset:64
	global_store_dwordx4 v[234:235], v[192:195], off offset:512
	global_store_dwordx4 v[234:235], v[196:199], off offset:576
	s_waitcnt lgkmcnt(0)
	v_pk_mul_f32 v[200:201], v[76:77], v[222:223] op_sel_hi:[1,0]
	v_pk_mul_f32 v[202:203], v[78:79], v[222:223] op_sel_hi:[1,0]
	v_pk_mul_f32 v[204:205], v[72:73], v[222:223] op_sel_hi:[1,0]
	v_pk_mul_f32 v[206:207], v[74:75], v[222:223] op_sel_hi:[1,0]
	v_pk_mul_f32 v[208:209], v[68:69], v[222:223] op_sel_hi:[1,0]
	v_pk_mul_f32 v[210:211], v[70:71], v[222:223] op_sel_hi:[1,0]
	v_pk_mul_f32 v[212:213], v[64:65], v[222:223] op_sel_hi:[1,0]
	v_pk_mul_f32 v[214:215], v[66:67], v[222:223] op_sel_hi:[1,0]
	v_pk_mul_f32 v[200:201], v[168:169], v[200:201]
	v_pk_mul_f32 v[202:203], v[170:171], v[202:203]
	v_pk_mul_f32 v[204:205], v[172:173], v[204:205]
	v_pk_mul_f32 v[206:207], v[174:175], v[206:207]
	v_pk_mul_f32 v[208:209], v[176:177], v[208:209]
	v_pk_mul_f32 v[210:211], v[178:179], v[210:211]
	v_pk_mul_f32 v[212:213], v[180:181], v[212:213]
	v_pk_mul_f32 v[214:215], v[182:183], v[214:215]
	s_mov_b64 s[4:5], 0x30000
	v_lshl_add_u64 v[234:235], v[232:233], 0, s[4:5]
	global_store_dwordx4 v[234:235], v[200:203], off
	global_store_dwordx4 v[234:235], v[204:207], off offset:64
	global_store_dwordx4 v[234:235], v[208:211], off offset:512
	global_store_dwordx4 v[234:235], v[212:215], off offset:576
	s_waitcnt lgkmcnt(0)
	s_barrier
;     __device__ __forceinline__ void fused(f32x4 (&acc)[2][2][4][2], const Unit& u, int wr, int wc, int fr, int fq, LAS unsigned char* lds, int wid, int lane) const {
;     ...
;         f32x4 fgv[2][2];
; #pragma unroll
;         for (int bj = 0; bj < 2; ++bj)
; #pragma unroll
;             for (int n = 0; n < 2; ++n) fgv[bj][n] = *(const f32x4*)(fg + col0 + bj * HALF + n * 16);
; #pragma unroll
;         for (int ai = 0; ai < 2; ++ai)
; #pragma unroll
;             for (int m = 0; m < 4; ++m) { const int rl = ai * HALF + wr * 64 + m * 16 + fr; const float r = S[rl]; const size_t off = (size_t)(u.pm * BM + rl) * DM + col0;
; #pragma unroll
;                 for (int bj = 0; bj < 2; ++bj)
; #pragma unroll
;                     for (int n = 0; n < 2; ++n) *(f32x4*)(out + off + bj * HALF + n * 16) = acc[ai][bj][m][n] * r * fgv[bj][n]; }
	ds_read_b32 v224, v238 offset:4608
	ds_read_b32 v226, v238 offset:4672
	ds_read_b32 v228, v238 offset:4736
	ds_read_b32 v230, v238 offset:4800
	s_waitcnt lgkmcnt(3)
	v_pk_mul_f32 v[184:185], v[60:61], v[224:225] op_sel_hi:[1,0]
	v_pk_mul_f32 v[186:187], v[62:63], v[224:225] op_sel_hi:[1,0]
	v_pk_mul_f32 v[188:189], v[56:57], v[224:225] op_sel_hi:[1,0]
	v_pk_mul_f32 v[190:191], v[58:59], v[224:225] op_sel_hi:[1,0]
	v_pk_mul_f32 v[192:193], v[52:53], v[224:225] op_sel_hi:[1,0]
	v_pk_mul_f32 v[194:195], v[54:55], v[224:225] op_sel_hi:[1,0]
	v_pk_mul_f32 v[196:197], v[48:49], v[224:225] op_sel_hi:[1,0]
	v_pk_mul_f32 v[198:199], v[50:51], v[224:225] op_sel_hi:[1,0]
	v_pk_mul_f32 v[184:185], v[168:169], v[184:185]
	v_pk_mul_f32 v[186:187], v[170:171], v[186:187]
	v_pk_mul_f32 v[188:189], v[172:173], v[188:189]
	v_pk_mul_f32 v[190:191], v[174:175], v[190:191]
	v_pk_mul_f32 v[192:193], v[176:177], v[192:193]
	v_pk_mul_f32 v[194:195], v[178:179], v[194:195]
	v_pk_mul_f32 v[196:197], v[180:181], v[196:197]
	v_pk_mul_f32 v[198:199], v[182:183], v[198:199]
	s_mov_b64 s[4:5], 0x80000
	v_lshl_add_u64 v[234:235], v[232:233], 0, s[4:5]
	global_store_dwordx4 v[234:235], v[184:187], off
	global_store_dwordx4 v[234:235], v[188:191], off offset:64
	global_store_dwordx4 v[234:235], v[192:195], off offset:512
	global_store_dwordx4 v[234:235], v[196:199], off offset:576
	s_waitcnt lgkmcnt(2)
	v_pk_mul_f32 v[200:201], v[44:45], v[226:227] op_sel_hi:[1,0]
	v_pk_mul_f32 v[202:203], v[46:47], v[226:227] op_sel_hi:[1,0]
	v_pk_mul_f32 v[204:205], v[40:41], v[226:227] op_sel_hi:[1,0]
	v_pk_mul_f32 v[206:207], v[42:43], v[226:227] op_sel_hi:[1,0]
	v_pk_mul_f32 v[208:209], v[36:37], v[226:227] op_sel_hi:[1,0]
	v_pk_mul_f32 v[210:211], v[38:39], v[226:227] op_sel_hi:[1,0]
	v_pk_mul_f32 v[212:213], v[32:33], v[226:227] op_sel_hi:[1,0]
	v_pk_mul_f32 v[214:215], v[34:35], v[226:227] op_sel_hi:[1,0]
	v_pk_mul_f32 v[200:201], v[168:169], v[200:201]
	v_pk_mul_f32 v[202:203], v[170:171], v[202:203]
	v_pk_mul_f32 v[204:205], v[172:173], v[204:205]
	v_pk_mul_f32 v[206:207], v[174:175], v[206:207]
	v_pk_mul_f32 v[208:209], v[176:177], v[208:209]
	v_pk_mul_f32 v[210:211], v[178:179], v[210:211]
	v_pk_mul_f32 v[212:213], v[180:181], v[212:213]
	v_pk_mul_f32 v[214:215], v[182:183], v[214:215]
	s_mov_b64 s[4:5], 0x90000
	v_lshl_add_u64 v[234:235], v[232:233], 0, s[4:5]
	global_store_dwordx4 v[234:235], v[200:203], off
	global_store_dwordx4 v[234:235], v[204:207], off offset:64
	global_store_dwordx4 v[234:235], v[208:211], off offset:512
	global_store_dwordx4 v[234:235], v[212:215], off offset:576
	s_waitcnt lgkmcnt(1)
	v_pk_mul_f32 v[184:185], v[28:29], v[228:229] op_sel_hi:[1,0]
	v_pk_mul_f32 v[186:187], v[30:31], v[228:229] op_sel_hi:[1,0]
	v_pk_mul_f32 v[188:189], v[24:25], v[228:229] op_sel_hi:[1,0]
	v_pk_mul_f32 v[190:191], v[26:27], v[228:229] op_sel_hi:[1,0]
	v_pk_mul_f32 v[192:193], v[20:21], v[228:229] op_sel_hi:[1,0]
	v_pk_mul_f32 v[194:195], v[22:23], v[228:229] op_sel_hi:[1,0]
	v_pk_mul_f32 v[196:197], v[16:17], v[228:229] op_sel_hi:[1,0]
	v_pk_mul_f32 v[198:199], v[18:19], v[228:229] op_sel_hi:[1,0]
	v_pk_mul_f32 v[184:185], v[168:169], v[184:185]
	v_pk_mul_f32 v[186:187], v[170:171], v[186:187]
	v_pk_mul_f32 v[188:189], v[172:173], v[188:189]
	v_pk_mul_f32 v[190:191], v[174:175], v[190:191]
	v_pk_mul_f32 v[192:193], v[176:177], v[192:193]
	v_pk_mul_f32 v[194:195], v[178:179], v[194:195]
	v_pk_mul_f32 v[196:197], v[180:181], v[196:197]
	v_pk_mul_f32 v[198:199], v[182:183], v[198:199]
	s_mov_b64 s[4:5], 0xa0000
	v_lshl_add_u64 v[234:235], v[232:233], 0, s[4:5]
	global_store_dwordx4 v[234:235], v[184:187], off
	global_store_dwordx4 v[234:235], v[188:191], off offset:64
	global_store_dwordx4 v[234:235], v[192:195], off offset:512
	global_store_dwordx4 v[234:235], v[196:199], off offset:576
	s_waitcnt lgkmcnt(0)
	v_pk_mul_f32 v[200:201], v[148:149], v[230:231] op_sel_hi:[1,0]
	v_pk_mul_f32 v[202:203], v[146:147], v[230:231] op_sel_hi:[1,0]
	v_pk_mul_f32 v[204:205], v[136:137], v[230:231] op_sel_hi:[1,0]
	v_pk_mul_f32 v[206:207], v[138:139], v[230:231] op_sel_hi:[1,0]
	v_pk_mul_f32 v[208:209], v[132:133], v[230:231] op_sel_hi:[1,0]
	v_pk_mul_f32 v[210:211], v[134:135], v[230:231] op_sel_hi:[1,0]
	v_pk_mul_f32 v[212:213], v[130:131], v[230:231] op_sel_hi:[1,0]
	v_pk_mul_f32 v[214:215], v[128:129], v[230:231] op_sel_hi:[1,0]
	v_pk_mul_f32 v[200:201], v[168:169], v[200:201]
	v_pk_mul_f32 v[202:203], v[170:171], v[202:203]
	v_pk_mul_f32 v[204:205], v[172:173], v[204:205]
	v_pk_mul_f32 v[206:207], v[174:175], v[206:207]
	v_pk_mul_f32 v[208:209], v[176:177], v[208:209]
	v_pk_mul_f32 v[210:211], v[178:179], v[210:211]
	v_pk_mul_f32 v[212:213], v[180:181], v[212:213]
	v_pk_mul_f32 v[214:215], v[182:183], v[214:215]
	s_mov_b64 s[4:5], 0xb0000
	v_lshl_add_u64 v[234:235], v[232:233], 0, s[4:5]
	global_store_dwordx4 v[234:235], v[200:203], off
	global_store_dwordx4 v[234:235], v[204:207], off offset:64
	global_store_dwordx4 v[234:235], v[208:211], off offset:512
	global_store_dwordx4 v[234:235], v[212:215], off offset:576
